# SSD-B item tail: 16 gain-vector loads hoisted before the unrolled normalize/store loop, ds_reads batched, no waits on stores
# baseline (speedup 1.0000x reference)
.LBB0_966:
	global_load_dwordx4 v[98:101], v[6:7], off
	global_load_dwordx4 v[102:105], v[6:7], off offset:64
	global_load_dwordx4 v[106:109], v[6:7], off offset:128
	global_load_dwordx4 v[110:113], v[6:7], off offset:192
	global_load_dwordx4 v[114:117], v[6:7], off offset:256
	global_load_dwordx4 v[118:121], v[6:7], off offset:320
	global_load_dwordx4 v[122:125], v[6:7], off offset:384
	global_load_dwordx4 v[126:129], v[6:7], off offset:448
	global_load_dwordx4 v[130:133], v[6:7], off offset:512
	global_load_dwordx4 v[134:137], v[6:7], off offset:576
	global_load_dwordx4 v[138:141], v[6:7], off offset:640
	global_load_dwordx4 v[142:145], v[6:7], off offset:704
	global_load_dwordx4 v[146:149], v[6:7], off offset:768
	global_load_dwordx4 v[150:153], v[6:7], off offset:832
	global_load_dwordx4 v[154:157], v[6:7], off offset:896
	global_load_dwordx4 v[158:161], v[6:7], off offset:960
	ds_read_b128 v[168:171], v65
	ds_read_b128 v[172:175], v65 offset:1024
	ds_read_b128 v[176:179], v65 offset:2048
	ds_read_b128 v[180:183], v65 offset:3072
	v_lshl_add_u64 v[16:17], v[2:3], 0, s[6:7]
	v_add_co_u32_e32 v16, vcc, s34, v16
	s_add_u32 s6, s6, 0x80
	s_addc_u32 s7, s7, 0
	s_nop 0
	v_addc_co_u32_e32 v17, vcc, 0, v17, vcc
	s_waitcnt lgkmcnt(3)
	v_pk_mul_f32 v[168:169], v[4:5], v[168:169]
	v_pk_mul_f32 v[170:171], v[4:5], v[170:171]
	s_waitcnt vmcnt(0)
	v_pk_mul_f32 v[168:169], v[98:99], v[168:169]
	v_pk_mul_f32 v[170:171], v[170:171], v[100:101]
	v_cvt_pk_bf16_f32 v168, v168, v169
	v_cvt_pk_bf16_f32 v169, v170, v171
	global_store_dwordx2 v[16:17], v[168:169], off offset:1536
	s_waitcnt lgkmcnt(2)
	v_pk_mul_f32 v[172:173], v[4:5], v[172:173]
	v_pk_mul_f32 v[174:175], v[4:5], v[174:175]
	v_pk_mul_f32 v[172:173], v[102:103], v[172:173]
	v_pk_mul_f32 v[174:175], v[174:175], v[104:105]
	v_cvt_pk_bf16_f32 v172, v172, v173
	v_cvt_pk_bf16_f32 v173, v174, v175
	global_store_dwordx2 v[16:17], v[172:173], off offset:1568
	s_waitcnt lgkmcnt(1)
	v_pk_mul_f32 v[176:177], v[4:5], v[176:177]
	v_pk_mul_f32 v[178:179], v[4:5], v[178:179]
	v_pk_mul_f32 v[176:177], v[106:107], v[176:177]
	v_pk_mul_f32 v[178:179], v[178:179], v[108:109]
	v_cvt_pk_bf16_f32 v176, v176, v177
	v_cvt_pk_bf16_f32 v177, v178, v179
	global_store_dwordx2 v[16:17], v[176:177], off offset:1600
	s_waitcnt lgkmcnt(0)
	v_pk_mul_f32 v[180:181], v[4:5], v[180:181]
	v_pk_mul_f32 v[182:183], v[4:5], v[182:183]
	v_pk_mul_f32 v[180:181], v[110:111], v[180:181]
	v_pk_mul_f32 v[182:183], v[182:183], v[112:113]
	v_cvt_pk_bf16_f32 v180, v180, v181
	v_cvt_pk_bf16_f32 v181, v182, v183
	global_store_dwordx2 v[16:17], v[180:181], off offset:1632
	v_add_u32_e32 v65, 0x8000, v65
	ds_read_b128 v[168:171], v65
	ds_read_b128 v[172:175], v65 offset:1024
	ds_read_b128 v[176:179], v65 offset:2048
	ds_read_b128 v[180:183], v65 offset:3072
	v_lshl_add_u64 v[16:17], v[2:3], 0, s[6:7]
	v_add_co_u32_e32 v16, vcc, s34, v16
	s_add_u32 s6, s6, 0x80
	s_addc_u32 s7, s7, 0
	s_nop 0
	v_addc_co_u32_e32 v17, vcc, 0, v17, vcc
	s_waitcnt lgkmcnt(3)
	v_pk_mul_f32 v[168:169], v[4:5], v[168:169]
	v_pk_mul_f32 v[170:171], v[4:5], v[170:171]
	v_pk_mul_f32 v[168:169], v[114:115], v[168:169]
	v_pk_mul_f32 v[170:171], v[170:171], v[116:117]
	v_cvt_pk_bf16_f32 v168, v168, v169
	v_cvt_pk_bf16_f32 v169, v170, v171
	global_store_dwordx2 v[16:17], v[168:169], off offset:1536
	s_waitcnt lgkmcnt(2)
	v_pk_mul_f32 v[172:173], v[4:5], v[172:173]
	v_pk_mul_f32 v[174:175], v[4:5], v[174:175]
	v_pk_mul_f32 v[172:173], v[118:119], v[172:173]
	v_pk_mul_f32 v[174:175], v[174:175], v[120:121]
	v_cvt_pk_bf16_f32 v172, v172, v173
	v_cvt_pk_bf16_f32 v173, v174, v175
	global_store_dwordx2 v[16:17], v[172:173], off offset:1568
	s_waitcnt lgkmcnt(1)
	v_pk_mul_f32 v[176:177], v[4:5], v[176:177]
	v_pk_mul_f32 v[178:179], v[4:5], v[178:179]
	v_pk_mul_f32 v[176:177], v[122:123], v[176:177]
	v_pk_mul_f32 v[178:179], v[178:179], v[124:125]
	v_cvt_pk_bf16_f32 v176, v176, v177
	v_cvt_pk_bf16_f32 v177, v178, v179
	global_store_dwordx2 v[16:17], v[176:177], off offset:1600
	s_waitcnt lgkmcnt(0)
	v_pk_mul_f32 v[180:181], v[4:5], v[180:181]
	v_pk_mul_f32 v[182:183], v[4:5], v[182:183]
	v_pk_mul_f32 v[180:181], v[126:127], v[180:181]
	v_pk_mul_f32 v[182:183], v[182:183], v[128:129]
	v_cvt_pk_bf16_f32 v180, v180, v181
	v_cvt_pk_bf16_f32 v181, v182, v183
	global_store_dwordx2 v[16:17], v[180:181], off offset:1632
	v_add_u32_e32 v65, 0x8000, v65
	ds_read_b128 v[168:171], v65
	ds_read_b128 v[172:175], v65 offset:1024
	ds_read_b128 v[176:179], v65 offset:2048
	ds_read_b128 v[180:183], v65 offset:3072
	v_lshl_add_u64 v[16:17], v[2:3], 0, s[6:7]
	v_add_co_u32_e32 v16, vcc, s34, v16
	s_add_u32 s6, s6, 0x80
	s_addc_u32 s7, s7, 0
	s_nop 0
	v_addc_co_u32_e32 v17, vcc, 0, v17, vcc
	s_waitcnt lgkmcnt(3)
	v_pk_mul_f32 v[168:169], v[4:5], v[168:169]
	v_pk_mul_f32 v[170:171], v[4:5], v[170:171]
	v_pk_mul_f32 v[168:169], v[130:131], v[168:169]
	v_pk_mul_f32 v[170:171], v[170:171], v[132:133]
	v_cvt_pk_bf16_f32 v168, v168, v169
	v_cvt_pk_bf16_f32 v169, v170, v171
	global_store_dwordx2 v[16:17], v[168:169], off offset:1536
	s_waitcnt lgkmcnt(2)
	v_pk_mul_f32 v[172:173], v[4:5], v[172:173]
	v_pk_mul_f32 v[174:175], v[4:5], v[174:175]
	v_pk_mul_f32 v[172:173], v[134:135], v[172:173]
	v_pk_mul_f32 v[174:175], v[174:175], v[136:137]
	v_cvt_pk_bf16_f32 v172, v172, v173
	v_cvt_pk_bf16_f32 v173, v174, v175
	global_store_dwordx2 v[16:17], v[172:173], off offset:1568
	s_waitcnt lgkmcnt(1)
	v_pk_mul_f32 v[176:177], v[4:5], v[176:177]
	v_pk_mul_f32 v[178:179], v[4:5], v[178:179]
	v_pk_mul_f32 v[176:177], v[138:139], v[176:177]
	v_pk_mul_f32 v[178:179], v[178:179], v[140:141]
	v_cvt_pk_bf16_f32 v176, v176, v177
	v_cvt_pk_bf16_f32 v177, v178, v179
	global_store_dwordx2 v[16:17], v[176:177], off offset:1600
	s_waitcnt lgkmcnt(0)
	v_pk_mul_f32 v[180:181], v[4:5], v[180:181]
	v_pk_mul_f32 v[182:183], v[4:5], v[182:183]
	v_pk_mul_f32 v[180:181], v[142:143], v[180:181]
	v_pk_mul_f32 v[182:183], v[182:183], v[144:145]
	v_cvt_pk_bf16_f32 v180, v180, v181
	v_cvt_pk_bf16_f32 v181, v182, v183
	global_store_dwordx2 v[16:17], v[180:181], off offset:1632
	v_add_u32_e32 v65, 0x8000, v65
	ds_read_b128 v[168:171], v65
	ds_read_b128 v[172:175], v65 offset:1024
	ds_read_b128 v[176:179], v65 offset:2048
	ds_read_b128 v[180:183], v65 offset:3072
	v_lshl_add_u64 v[16:17], v[2:3], 0, s[6:7]
	v_add_co_u32_e32 v16, vcc, s34, v16
	s_add_u32 s6, s6, 0x80
	s_addc_u32 s7, s7, 0
	s_nop 0
	v_addc_co_u32_e32 v17, vcc, 0, v17, vcc
	s_waitcnt lgkmcnt(3)
	v_pk_mul_f32 v[168:169], v[4:5], v[168:169]
	v_pk_mul_f32 v[170:171], v[4:5], v[170:171]
	v_pk_mul_f32 v[168:169], v[146:147], v[168:169]
	v_pk_mul_f32 v[170:171], v[170:171], v[148:149]
	v_cvt_pk_bf16_f32 v168, v168, v169
	v_cvt_pk_bf16_f32 v169, v170, v171
	global_store_dwordx2 v[16:17], v[168:169], off offset:1536
	s_waitcnt lgkmcnt(2)
	v_pk_mul_f32 v[172:173], v[4:5], v[172:173]
	v_pk_mul_f32 v[174:175], v[4:5], v[174:175]
	v_pk_mul_f32 v[172:173], v[150:151], v[172:173]
	v_pk_mul_f32 v[174:175], v[174:175], v[152:153]
	v_cvt_pk_bf16_f32 v172, v172, v173
	v_cvt_pk_bf16_f32 v173, v174, v175
	global_store_dwordx2 v[16:17], v[172:173], off offset:1568
	s_waitcnt lgkmcnt(1)
	v_pk_mul_f32 v[176:177], v[4:5], v[176:177]
	v_pk_mul_f32 v[178:179], v[4:5], v[178:179]
	v_pk_mul_f32 v[176:177], v[154:155], v[176:177]
	v_pk_mul_f32 v[178:179], v[178:179], v[156:157]
	v_cvt_pk_bf16_f32 v176, v176, v177
	v_cvt_pk_bf16_f32 v177, v178, v179
	global_store_dwordx2 v[16:17], v[176:177], off offset:1600
	s_waitcnt lgkmcnt(0)
	v_pk_mul_f32 v[180:181], v[4:5], v[180:181]
	v_pk_mul_f32 v[182:183], v[4:5], v[182:183]
	v_pk_mul_f32 v[180:181], v[158:159], v[180:181]
	v_pk_mul_f32 v[182:183], v[182:183], v[160:161]
	v_cvt_pk_bf16_f32 v180, v180, v181
	v_cvt_pk_bf16_f32 v181, v182, v183
	global_store_dwordx2 v[16:17], v[180:181], off offset:1632
	v_add_u32_e32 v65, 0x8000, v65
	s_waitcnt lgkmcnt(0)
	s_barrier
